# NSA near-distance tiles (selected+window): bias gathered via clamped table address with -1e30 sentinel entry, no per-element mask ops; packed softmax arithmetic; prefetched QK/PV LDS reads
# speedup vs baseline: 1.0345x; 1.0049x over previous
; #define LAS __attribute__((address_space(3)))
; #define MFMA32(a, b, c) __builtin_amdgcn_mfma_f32_32x32x16_bf16((a), (b), (c), 0, 0, 0)
; DI void attn_scores(const LAS bf16_t* Ks, const bf16x8 (&qf)[4], int r, int h, f32x16 (&s)[2]) {
; #pragma unroll
;   for (int sub = 0; sub < 2; ++sub) {
;     f32x16 a;
; #pragma unroll
;     for (int i = 0; i < 16; ++i) a[i] = 0.f;
; #pragma unroll
;     for (int ks = 0; ks < 4; ++ks) { const bf16x8 kf = *(const LAS bf16x8*)(Ks + (sub * 32 + r) * KS_STRIDE + ks * 16 + 8 * h); a = MFMA32(kf, qf[ks], a); }
;     s[sub] = a;
;   }
; }
; DI void nsa_attn_phase(int wv, const P& p_, LAS unsigned char* lds) {
;     ...
;     { const unsigned long long selm = (unsigned long long)SELM[2 * (8 * wid + tl)] | ((unsigned long long)SELM[2 * (8 * wid + tl) + 1] << 32);
;       unsigned long long rem = (unsigned long long)UNI[0] | ((unsigned long long)UNI[1] << 32);
;       m = -1e30f; l = 0.f; zero_o(O);
;       const int jw0 = qi > 8 ? qi - 8 : 0;
; #pragma unroll 1
;       while (rem) {
;         const int j = __builtin_ctzll(rem); rem &= rem - 1ull;
;         kv_store(kvr, KsB[buf], VtB[buf], 68, 0, tid);
;         __syncthreads();
;         { const bool more = rem != 0ull; const int jn = more ? __builtin_ctzll(rem) : jw0;
;           const size_t go = (size_t)(b * SEQ + jn * 64) * ld + g * 64; kv_load(kvr, hb + go + (more ? 1536 : 2048), hb + go + (more ? 1792 : 2304), ld, tid); }
;         attn_tile(KsB[buf], VtB[buf], 68, qf, O, m, l, t, tw, 8, r, h, j * 64, 1, 0x7fffffff, ((selm >> j) & 1ull) != 0ull, btl);
.LBB0_773:
	s_add_i32 s0, 0, 0x22840
	v_mov_b32_e32 v0, s0
	s_waitcnt lgkmcnt(0)
	s_barrier
	ds_read_b64 v[0:1], v0
	v_ashrrev_i32_e32 v217, 3, v130
	v_lshlrev_b32_e32 v218, 3, v130
	v_and_b32_e32 v218, 56, v218
	v_mul_lo_u32 v216, v217, s90
	v_lshl_add_u32 v216, v218, 1, v216
	v_lshlrev_b32_e32 v220, 4, v130
	v_and_b32_e32 v220, 0x70, v220
	v_mul_u32_u24_e32 v221, 0x1600, v217
	v_add_u32_e32 v220, v221, v220
	v_mov_b32_e32 v221, 0
	v_and_b32_e32 v219, 8, v130
	v_lshrrev_b32_e32 v222, 1, v219
	v_or_b32_e32 v222, v218, v222
	v_mul_u32_u24_e32 v222, 0x88, v222
	v_lshlrev_b32_e32 v217, 1, v217
	v_and_b32_e32 v217, -4, v217
	v_add_u32_e32 v217, v222, v217
	v_mov_b32_e32 v218, v219
	v_add_u32_e32 v219, v134, v159
	ds_read_b32 v224, v158 offset:512
	v_and_b32_e32 v226, 3, v130
	v_mul_u32_u24_e32 v226, 0x210, v226
	v_add_u32_e32 v226, 0x21dfc, v226
	v_mov_b32_e32 v227, 0xf149f2ca
	ds_write_b32 v226, v227
	s_max_i32 s78, s95, 8
	s_add_i32 s71, s78, -8
	s_lshl_b32 s0, s40, 1
	s_add_u32 s50, s82, s0
	s_waitcnt lgkmcnt(0)
	v_readfirstlane_b32 s60, v0
	v_cmp_eq_u64_e32 vcc, 0, v[0:1]
	v_mul_u32_u24_e32 v0, 0x44, v149
	s_mov_b32 s44, 0xf149f2ca
	v_readfirstlane_b32 s61, v1
	s_addc_u32 s57, s83, 0
	v_lshlrev_b32_e32 v164, 1, v0
	s_cbranch_vccnz .LBB0_791
	v_or_b32_e32 v0, s4, v157
	v_lshl_add_u32 v0, v0, 3, 0
	v_add_u32_e32 v0, 0x22640, v0
	ds_read_b64 v[136:137], v0
	v_mov_b32_e32 v46, v32
	v_mov_b32_e32 v47, v32
	v_mov_b32_e32 v33, v32
	v_mov_b32_e32 v34, v32
	v_mov_b32_e32 v35, v32
	v_mov_b32_e32 v36, v32
	v_mov_b32_e32 v37, v32
	v_mov_b32_e32 v38, v32
	v_mov_b32_e32 v39, v32
	v_mov_b32_e32 v40, v32
	v_mov_b32_e32 v41, v32
	v_mov_b32_e32 v42, v32
	v_mov_b32_e32 v43, v32
	v_mov_b32_e32 v44, v32
	v_mov_b32_e32 v45, v32
	v_mov_b64_e32 v[64:65], v[46:47]
	v_lshlrev_b32_e32 v144, 2, v145
	v_mov_b64_e32 v[62:63], v[44:45]
	v_mov_b64_e32 v[60:61], v[42:43]
	v_mov_b64_e32 v[58:59], v[40:41]
	v_mov_b64_e32 v[56:57], v[38:39]
	v_mov_b64_e32 v[54:55], v[36:37]
	v_mov_b64_e32 v[52:53], v[34:35]
	v_mov_b64_e32 v[50:51], v[32:33]
	v_mov_b64_e32 v[48:49], v[46:47]
	s_sub_i32 s79, s87, 63
	v_not_b32_e32 v146, v144
	v_or_b32_e32 v148, 2, v144
	v_or_b32_e32 v149, 3, v144
	v_or_b32_e32 v150, 8, v144
	v_or_b32_e32 v151, 9, v144
	v_or_b32_e32 v152, 10, v144
	v_or_b32_e32 v153, 11, v144
	v_or_b32_e32 v154, 16, v144
	v_or_b32_e32 v155, 17, v144
	v_or_b32_e32 v165, 18, v144
	v_or_b32_e32 v166, 19, v144
	v_or_b32_e32 v167, 24, v144
	v_or_b32_e32 v168, 25, v144
	v_or_b32_e32 v169, 26, v144
	v_or_b32_e32 v170, 27, v144
	s_mov_b32 s70, 0
	v_mov_b32_e32 v171, 0xf149f2ca
	v_mov_b32_e32 v143, 0
	v_mov_b64_e32 v[46:47], v[44:45]
	v_mov_b64_e32 v[44:45], v[42:43]
	v_mov_b64_e32 v[42:43], v[40:41]
	v_mov_b64_e32 v[40:41], v[38:39]
	v_mov_b64_e32 v[38:39], v[36:37]
	v_mov_b64_e32 v[36:37], v[34:35]
	v_mov_b64_e32 v[34:35], v[32:33]
.LBB0_775:
	s_add_u32 s0, s60, -1
	s_addc_u32 s1, s61, -1
	s_ff1_i32_b64 s8, s[60:61]
	s_and_b64 s[60:61], s[0:1], s[60:61]
	s_cmp_eq_u32 s70, 1
	s_cselect_b32 s0, s58, 0
	s_cselect_b32 s84, s59, s81
	v_add_u32_e32 v3, s0, v216
	v_cmp_eq_u32_e32 vcc, 0, v218
	v_mov_b32_e32 v5, v32
	v_mov_b32_e32 v7, v32
	s_waitcnt vmcnt(1)
	ds_write_b128 v3, v[126:129]
	s_waitcnt vmcnt(0)
	v_cndmask_b32_e32 v3, v122, v124, vcc
	v_cndmask_b32_e32 v4, v123, v125, vcc
	v_add_u32_e32 v0, s84, v217
	v_add_u32_e32 v225, s0, v219
	v_mov_b32_dpp v5, v3 row_ror:8 row_mask:0xf bank_mask:0xf
	v_mov_b32_dpp v7, v4 row_ror:8 row_mask:0xf bank_mask:0xf
	v_cndmask_b32_e32 v4, v5, v122, vcc
	v_cndmask_b32_e32 v5, v124, v5, vcc
	v_cndmask_b32_e32 v6, v7, v123, vcc
	v_cndmask_b32_e32 v3, v125, v7, vcc
	v_lshlrev_b32_e32 v1, 16, v5
	v_lshrrev_b32_e32 v2, 16, v4
	v_and_or_b32 v1, v4, s89, v1
	v_and_or_b32 v2, v5, s88, v2
	ds_write2_b32 v0, v1, v2 offset1:34
	v_lshlrev_b32_e32 v1, 16, v3
	v_lshrrev_b32_e32 v2, 16, v6
	v_and_or_b32 v1, v6, s89, v1
	v_and_or_b32 v2, v3, s88, v2
	ds_write2_b32 v0, v1, v2 offset0:68 offset1:102
	s_waitcnt lgkmcnt(0)
	s_barrier
	ds_read_b128 v[0:3], v225
	ds_read_b128 v[4:7], v225 offset:32
	ds_read_b128 v[8:11], v225 offset:64
	ds_read_b128 v[12:15], v225 offset:96
	ds_read_b128 v[16:19], v225 offset:4608
	ds_read_b128 v[20:23], v225 offset:4640
	ds_read_b128 v[24:27], v225 offset:4672
	ds_read_b128 v[28:31], v225 offset:4704
	s_cmp_eq_u64 s[60:61], 0
	s_cselect_b64 s[64:65], -1, 0
	s_ff1_i32_b64 s6, s[60:61]
	s_and_b64 s[0:1], s[64:65], exec
	s_cselect_b32 s0, s71, s6
	s_movk_i32 s1, 0xc00
	s_movk_i32 s6, 0x1200
	s_cselect_b32 s1, 0x1000, s1
	s_cselect_b32 s6, s6, 0xe00
	s_lshl_b32 s0, s0, 6
	s_add_i32 s0, s0, s93
	s_mul_hi_u32 s7, s0, 0x1600
	s_mulk_i32 s0, 0x1600
	s_add_u32 s9, s50, s0
	s_addc_u32 s7, s57, s7
	s_add_u32 s0, s9, s1
	s_addc_u32 s1, s7, 0
	s_add_u32 s6, s9, s6
	s_addc_u32 s7, s7, 0
	v_lshl_add_u64 v[226:227], v[220:221], 0, s[0:1]
	v_lshl_add_u64 v[230:231], v[220:221], 0, s[6:7]
	s_lshl_b32 s10, s8, 6
	global_load_dwordx4 v[126:129], v[226:227], off
	global_load_dwordx4 v[122:125], v[230:231], off
	v_lshrrev_b64 v[244:245], s8, v[136:137]
	s_sub_i32 s8, s79, s10
	s_cmpk_gt_i32 s8, 0x7f
	s_cselect_b64 s[0:1], -1, 0
	s_cmpk_lt_i32 s8, 0x80
	s_cselect_b64 s[8:9], -1, 0
	s_sub_i32 s11, s10, s87
	s_cmp_eq_u32 s11, 0x80000008
	s_cselect_b64 s[12:13], -1, 0
	v_and_b32_e32 v244, 1, v244
	s_or_b64 s[12:13], s[8:9], s[12:13]
	v_cmp_eq_u32_e64 s[6:7], 1, v244
	s_mov_b64 s[8:9], -1
	s_waitcnt lgkmcnt(4)
	v_mfma_f32_32x32x16_bf16 v[82:97], v[0:3], v[106:109], 0
	v_mfma_f32_32x32x16_bf16 v[82:97], v[4:7], v[110:113], v[82:97]
	v_mfma_f32_32x32x16_bf16 v[82:97], v[8:11], v[114:117], v[82:97]
	v_mfma_f32_32x32x16_bf16 v[82:97], v[12:15], v[118:121], v[82:97]
	s_waitcnt lgkmcnt(0)
	v_mfma_f32_32x32x16_bf16 v[66:81], v[16:19], v[106:109], 0
	v_mfma_f32_32x32x16_bf16 v[66:81], v[20:23], v[110:113], v[66:81]
	v_mfma_f32_32x32x16_bf16 v[66:81], v[24:27], v[114:117], v[66:81]
	v_mfma_f32_32x32x16_bf16 v[66:81], v[28:31], v[118:121], v[66:81]
	s_and_b64 vcc, exec, s[12:13]
	s_cbranch_vccz .LBB0_779
	s_and_b64 vcc, exec, s[8:9]
	s_cbranch_vccnz .LBB0_782

; DI int crow(int reg, int h) { return (reg & 3) + 8 * (reg >> 2) + 4 * h; }
; DI void attn_logits(f32x16 (&s)[2], int t, int tw, int nt, int h, int base, int stride, int dmax, bool ok, const LAS float* btl) {
;     ...
;   } else {
; #pragma unroll
;     for (int sub = 0; sub < 2; ++sub)
; #pragma unroll
;       for (int reg = 0; reg < 16; ++reg) {
;         const int kk = sub * 32 + crow(reg, h); const int d = t - (base + kk * stride);
;         const bool valid = (d >= 0) && (d < dmax) && ok;
;         const int di = d < 0 ? 0 : (d > 128 ? 128 : d);
;         const float bsv = btl[di];
;         const float x = s[sub][reg] * QK_SCALE2 + bsv;
;         s[sub][reg] = valid ? x : -1e30f;
;       }
;   }
; DI void attn_tile(const LAS bf16_t* Ks, const LAS bf16_t* Vt, int vstride, const bf16x8 (&qf)[4], f32x16 (&O)[2], float& m, float& l,
;                   int t, int tw, int nt, int r, int h, int base, int stride, int dmax, bool ok, const LAS float* btl) {
;     ...
;     attn_logits(s, t, tw, nt, h, base, stride, dmax, ok, btl);
;     float mx = -1e30f;
; #pragma unroll
;     for (int sub = 0; sub < 2; ++sub)
; #pragma unroll
;       for (int reg = 0; reg < 16; ++reg) mx = fmaxf(mx, s[sub][reg]);
;     mx = fmaxf(mx, __shfl_xor(mx, 32));
;     mn = fmaxf(m, mx);
.Lsel_near_new:
	v_subrev_u32_e32 v172, s10, v147
	v_sub_u32_e32 v172, v172, v144
	v_lshl_add_u32 v184, v172, 2, v158
	v_add_u32_e32 v185, -4, v158
	v_add_u32_e32 v186, 0x200, v158
	v_cndmask_b32_e64 v186, v185, v186, s[6:7]
	v_med3_i32 v172, v184, v185, v186
	v_subrev_u32_e32 v173, 4, v184
	v_med3_i32 v173, v173, v185, v186
	v_subrev_u32_e32 v174, 8, v184
	v_med3_i32 v174, v174, v185, v186
	v_subrev_u32_e32 v175, 12, v184
	v_med3_i32 v175, v175, v185, v186
	v_subrev_u32_e32 v180, 32, v184
	v_med3_i32 v180, v180, v185, v186
	v_subrev_u32_e32 v181, 36, v184
	v_med3_i32 v181, v181, v185, v186
	v_subrev_u32_e32 v182, 40, v184
	v_med3_i32 v182, v182, v185, v186
	v_subrev_u32_e32 v183, 44, v184
	v_med3_i32 v183, v183, v185, v186
	ds_read_b32 v0, v172
	ds_read_b32 v1, v173
	ds_read_b32 v2, v174
	ds_read_b32 v3, v175
	ds_read_b32 v4, v180
	ds_read_b32 v5, v181
	ds_read_b32 v6, v182
	ds_read_b32 v7, v183
	v_subrev_u32_e32 v172, 64, v184
	v_med3_i32 v172, v172, v185, v186
	v_subrev_u32_e32 v173, 68, v184
	v_med3_i32 v173, v173, v185, v186
	v_subrev_u32_e32 v174, 72, v184
	v_med3_i32 v174, v174, v185, v186
	v_subrev_u32_e32 v175, 76, v184
	v_med3_i32 v175, v175, v185, v186
	v_subrev_u32_e32 v180, 96, v184
	v_med3_i32 v180, v180, v185, v186
	v_subrev_u32_e32 v181, 100, v184
	v_med3_i32 v181, v181, v185, v186
	v_subrev_u32_e32 v182, 104, v184
	v_med3_i32 v182, v182, v185, v186
	v_subrev_u32_e32 v183, 108, v184
	v_med3_i32 v183, v183, v185, v186
	ds_read_b32 v8, v172
	ds_read_b32 v9, v173
	ds_read_b32 v10, v174
	ds_read_b32 v11, v175
	ds_read_b32 v12, v180
	ds_read_b32 v13, v181
	ds_read_b32 v14, v182
	ds_read_b32 v15, v183
	s_waitcnt lgkmcnt(8)
	v_fmac_f32_e32 v0, 0x3e38aa3b, v82
	v_fmac_f32_e32 v1, 0x3e38aa3b, v83
	v_fmac_f32_e32 v2, 0x3e38aa3b, v84
	v_fmac_f32_e32 v3, 0x3e38aa3b, v85
	v_fmac_f32_e32 v4, 0x3e38aa3b, v86
	v_fmac_f32_e32 v5, 0x3e38aa3b, v87
	v_fmac_f32_e32 v6, 0x3e38aa3b, v88
	v_fmac_f32_e32 v7, 0x3e38aa3b, v89
	v_subrev_u32_e32 v172, 128, v184
	v_med3_i32 v172, v172, v185, v186
	v_subrev_u32_e32 v173, 132, v184
	v_med3_i32 v173, v173, v185, v186
	v_subrev_u32_e32 v174, 136, v184
	v_med3_i32 v174, v174, v185, v186
	v_subrev_u32_e32 v175, 140, v184
	v_med3_i32 v175, v175, v185, v186
	v_subrev_u32_e32 v180, 160, v184
	v_med3_i32 v180, v180, v185, v186
	v_subrev_u32_e32 v181, 164, v184
	v_med3_i32 v181, v181, v185, v186
	v_subrev_u32_e32 v182, 168, v184
	v_med3_i32 v182, v182, v185, v186
	v_subrev_u32_e32 v183, 172, v184
	v_med3_i32 v183, v183, v185, v186
	ds_read_b32 v16, v172
	ds_read_b32 v17, v173
	ds_read_b32 v18, v174
	ds_read_b32 v19, v175
	ds_read_b32 v20, v180
	ds_read_b32 v21, v181
	ds_read_b32 v22, v182
	ds_read_b32 v23, v183
	s_waitcnt lgkmcnt(8)
	v_fmac_f32_e32 v8, 0x3e38aa3b, v90
	v_fmac_f32_e32 v9, 0x3e38aa3b, v91
	v_fmac_f32_e32 v10, 0x3e38aa3b, v92
	v_fmac_f32_e32 v11, 0x3e38aa3b, v93
	v_fmac_f32_e32 v12, 0x3e38aa3b, v94
	v_fmac_f32_e32 v13, 0x3e38aa3b, v95
	v_fmac_f32_e32 v14, 0x3e38aa3b, v96
	v_fmac_f32_e32 v15, 0x3e38aa3b, v97
	v_subrev_u32_e32 v172, 192, v184
	v_med3_i32 v172, v172, v185, v186
	v_subrev_u32_e32 v173, 196, v184
	v_med3_i32 v173, v173, v185, v186
	v_subrev_u32_e32 v174, 200, v184
	v_med3_i32 v174, v174, v185, v186
	v_subrev_u32_e32 v175, 204, v184
	v_med3_i32 v175, v175, v185, v186
	v_subrev_u32_e32 v180, 224, v184
	v_med3_i32 v180, v180, v185, v186
	v_subrev_u32_e32 v181, 228, v184
	v_med3_i32 v181, v181, v185, v186
	v_subrev_u32_e32 v182, 232, v184
	v_med3_i32 v182, v182, v185, v186
	v_subrev_u32_e32 v183, 236, v184
	v_med3_i32 v183, v183, v185, v186
	ds_read_b32 v24, v172
	ds_read_b32 v25, v173
	ds_read_b32 v26, v174
	ds_read_b32 v27, v175
	ds_read_b32 v28, v180
	ds_read_b32 v29, v181
	ds_read_b32 v30, v182
	ds_read_b32 v31, v183
	s_waitcnt lgkmcnt(8)
	v_fmac_f32_e32 v16, 0x3e38aa3b, v66
	v_fmac_f32_e32 v17, 0x3e38aa3b, v67
	v_fmac_f32_e32 v18, 0x3e38aa3b, v68
	v_fmac_f32_e32 v19, 0x3e38aa3b, v69
	v_fmac_f32_e32 v20, 0x3e38aa3b, v70
	v_fmac_f32_e32 v21, 0x3e38aa3b, v71
	v_fmac_f32_e32 v22, 0x3e38aa3b, v72
	v_fmac_f32_e32 v23, 0x3e38aa3b, v73
	s_waitcnt lgkmcnt(0)
	v_fmac_f32_e32 v24, 0x3e38aa3b, v74
	v_fmac_f32_e32 v25, 0x3e38aa3b, v75
	v_fmac_f32_e32 v26, 0x3e38aa3b, v76
	v_fmac_f32_e32 v27, 0x3e38aa3b, v77
	v_fmac_f32_e32 v28, 0x3e38aa3b, v78
	v_fmac_f32_e32 v29, 0x3e38aa3b, v79
	v_fmac_f32_e32 v30, 0x3e38aa3b, v80
	v_fmac_f32_e32 v31, 0x3e38aa3b, v81
	v_max3_f32 v172, v0, s44, v1
	v_max3_f32 v172, v172, v2, v3
	v_max3_f32 v172, v172, v4, v5
	v_max3_f32 v172, v172, v6, v7
	v_max3_f32 v172, v172, v8, v9
	v_max3_f32 v172, v172, v10, v11
	v_max3_f32 v172, v172, v12, v13
	v_max3_f32 v172, v172, v14, v15
	v_max3_f32 v172, v172, v16, v17
	v_max3_f32 v172, v172, v18, v19
	v_max3_f32 v172, v172, v20, v21
	v_max3_f32 v172, v172, v22, v23
	v_max3_f32 v172, v172, v24, v25
	v_max3_f32 v172, v172, v26, v27
	v_max3_f32 v172, v172, v28, v29
	v_max3_f32 v172, v172, v30, v31
	ds_bpermute_b32 v173, v160, v172
	s_waitcnt lgkmcnt(0)
; DI void attn_tile(const LAS bf16_t* Ks, const LAS bf16_t* Vt, int vstride, const bf16x8 (&qf)[4], f32x16 (&O)[2], float& m, float& l,
;                   int t, int tw, int nt, int r, int h, int base, int stride, int dmax, bool ok, const LAS float* btl) {
;     ...
;     mx = fmaxf(mx, __shfl_xor(mx, 32));
;     mn = fmaxf(m, mx);
; #pragma unroll
;     for (int sub = 0; sub < 2; ++sub)
; #pragma unroll
;       for (int reg = 0; reg < 16; ++reg) { const float e = __builtin_amdgcn_exp2f(s[sub][reg] - mn); s[sub][reg] = e; ls += e; }
;   }
	v_max3_f32 v139, v171, v172, v173
	s_nop 0
	v_pk_add_f32 v[0:1], v[0:1], v[138:139] op_sel:[0,1] op_sel_hi:[1,1] neg_lo:[0,1] neg_hi:[0,1]
	v_pk_add_f32 v[2:3], v[2:3], v[138:139] op_sel:[0,1] op_sel_hi:[1,1] neg_lo:[0,1] neg_hi:[0,1]
	v_pk_add_f32 v[4:5], v[4:5], v[138:139] op_sel:[0,1] op_sel_hi:[1,1] neg_lo:[0,1] neg_hi:[0,1]
	v_pk_add_f32 v[6:7], v[6:7], v[138:139] op_sel:[0,1] op_sel_hi:[1,1] neg_lo:[0,1] neg_hi:[0,1]
	v_pk_add_f32 v[8:9], v[8:9], v[138:139] op_sel:[0,1] op_sel_hi:[1,1] neg_lo:[0,1] neg_hi:[0,1]
	v_pk_add_f32 v[10:11], v[10:11], v[138:139] op_sel:[0,1] op_sel_hi:[1,1] neg_lo:[0,1] neg_hi:[0,1]
	v_pk_add_f32 v[12:13], v[12:13], v[138:139] op_sel:[0,1] op_sel_hi:[1,1] neg_lo:[0,1] neg_hi:[0,1]
	v_pk_add_f32 v[14:15], v[14:15], v[138:139] op_sel:[0,1] op_sel_hi:[1,1] neg_lo:[0,1] neg_hi:[0,1]
	v_pk_add_f32 v[16:17], v[16:17], v[138:139] op_sel:[0,1] op_sel_hi:[1,1] neg_lo:[0,1] neg_hi:[0,1]
	v_pk_add_f32 v[18:19], v[18:19], v[138:139] op_sel:[0,1] op_sel_hi:[1,1] neg_lo:[0,1] neg_hi:[0,1]
	v_pk_add_f32 v[20:21], v[20:21], v[138:139] op_sel:[0,1] op_sel_hi:[1,1] neg_lo:[0,1] neg_hi:[0,1]
	v_pk_add_f32 v[22:23], v[22:23], v[138:139] op_sel:[0,1] op_sel_hi:[1,1] neg_lo:[0,1] neg_hi:[0,1]
	v_pk_add_f32 v[24:25], v[24:25], v[138:139] op_sel:[0,1] op_sel_hi:[1,1] neg_lo:[0,1] neg_hi:[0,1]
	v_pk_add_f32 v[26:27], v[26:27], v[138:139] op_sel:[0,1] op_sel_hi:[1,1] neg_lo:[0,1] neg_hi:[0,1]
	v_pk_add_f32 v[28:29], v[28:29], v[138:139] op_sel:[0,1] op_sel_hi:[1,1] neg_lo:[0,1] neg_hi:[0,1]
	v_pk_add_f32 v[30:31], v[30:31], v[138:139] op_sel:[0,1] op_sel_hi:[1,1] neg_lo:[0,1] neg_hi:[0,1]
	v_exp_f32_e32 v0, v0
	v_exp_f32_e32 v1, v1
	v_exp_f32_e32 v2, v2
	v_exp_f32_e32 v3, v3
	v_exp_f32_e32 v4, v4
	v_exp_f32_e32 v5, v5
	v_exp_f32_e32 v6, v6
	v_exp_f32_e32 v7, v7
	v_exp_f32_e32 v8, v8
	v_exp_f32_e32 v9, v9
	v_exp_f32_e32 v10, v10
	v_exp_f32_e32 v11, v11
	v_exp_f32_e32 v12, v12
	v_exp_f32_e32 v13, v13
	v_exp_f32_e32 v14, v14
	v_exp_f32_e32 v15, v15
	v_exp_f32_e32 v16, v16
	v_exp_f32_e32 v17, v17
	v_exp_f32_e32 v18, v18
	v_exp_f32_e32 v19, v19
	v_exp_f32_e32 v20, v20
	v_exp_f32_e32 v21, v21
	v_exp_f32_e32 v22, v22
	v_exp_f32_e32 v23, v23
	v_exp_f32_e32 v24, v24
	v_exp_f32_e32 v25, v25
	v_exp_f32_e32 v26, v26
	v_exp_f32_e32 v27, v27
	v_exp_f32_e32 v28, v28
	v_exp_f32_e32 v29, v29
	v_exp_f32_e32 v30, v30
	v_mov_b32_e32 v141, v31
	v_pk_add_f32 v[176:177], v[0:1], v[2:3]
	v_pk_add_f32 v[178:179], v[4:5], v[6:7]
	v_pk_add_f32 v[176:177], v[176:177], v[8:9]
	v_pk_add_f32 v[178:179], v[178:179], v[10:11]
	v_pk_add_f32 v[176:177], v[176:177], v[12:13]
	v_pk_add_f32 v[178:179], v[178:179], v[14:15]
	v_pk_add_f32 v[176:177], v[176:177], v[16:17]
	v_pk_add_f32 v[178:179], v[178:179], v[18:19]
	v_pk_add_f32 v[176:177], v[176:177], v[20:21]
	v_pk_add_f32 v[178:179], v[178:179], v[22:23]
	v_pk_add_f32 v[176:177], v[176:177], v[24:25]
	v_pk_add_f32 v[178:179], v[178:179], v[26:27]
	v_pk_add_f32 v[176:177], v[176:177], v[28:29]
	s_nop 0
	v_pk_add_f32 v[176:177], v[176:177], v[178:179]
	s_nop 0
	v_add_f32_e32 v140, v176, v177
	v_add_f32_e32 v140, v30, v140
	s_branch .LBB0_777
; DI int crow(int reg, int h) { return (reg & 3) + 8 * (reg >> 2) + 4 * h; }
; DI void attn_logits(f32x16 (&s)[2], int t, int tw, int nt, int h, int base, int stride, int dmax, bool ok, const LAS float* btl) {
;     ...
;   } else if (far) {
; #pragma unroll
;     for (int sub = 0; sub < 2; ++sub)
; #pragma unroll
;       for (int reg = 0; reg < 16; ++reg) {
;         const int kk = sub * 32 + crow(reg, h); const int d = t - (base + kk * stride);
;         const bool valid = (d >= 0) && (d < dmax) && ok;
;         s[sub][reg] = valid ? s[sub][reg] * QK_SCALE2 + bfar : -1e30f;
;       }
.LBB0_782:
	s_and_b64 vcc, exec, s[0:1]
	s_cbranch_vccz .Lsel_near_new
	v_subrev_u32_e32 v0, s10, v147
	v_sub_u32_e32 v206, v0, v144
	v_cmp_gt_u32_e32 vcc, s55, v206
	v_add_u32_e32 v205, v0, v146
	v_sub_u32_e32 v204, v0, v148
	v_sub_u32_e32 v203, v0, v149
	v_sub_u32_e32 v202, v0, v150
	v_sub_u32_e32 v193, v0, v151
	v_sub_u32_e32 v192, v0, v152
	v_sub_u32_e32 v191, v0, v153
	v_sub_u32_e32 v190, v0, v154
	v_sub_u32_e32 v189, v0, v155
	v_sub_u32_e32 v188, v0, v165
	v_sub_u32_e32 v187, v0, v166
	v_sub_u32_e32 v186, v0, v167
	v_sub_u32_e32 v185, v0, v168
	v_sub_u32_e32 v184, v0, v169
	v_sub_u32_e32 v183, v0, v170
	v_subrev_u32_e32 v182, 32, v206
	s_and_b64 s[8:9], s[6:7], vcc
	s_mov_b64 s[90:91], -1
	s_and_b64 vcc, exec, s[0:1]
	v_cmp_gt_u32_e64 s[42:43], s55, v205
	v_cmp_gt_u32_e64 s[40:41], s55, v204
	v_cmp_gt_u32_e64 s[38:39], s55, v203
	v_cmp_gt_u32_e64 s[36:37], s55, v202
	v_cmp_gt_u32_e64 s[34:35], s55, v193
	v_cmp_gt_u32_e64 s[30:31], s55, v192
	v_cmp_gt_u32_e64 s[26:27], s55, v191
	v_cmp_gt_u32_e64 s[24:25], s55, v190
	v_cmp_gt_u32_e64 s[22:23], s55, v189
	v_cmp_gt_u32_e64 s[20:21], s55, v188
	v_cmp_gt_u32_e64 s[18:19], s55, v187
	v_cmp_gt_u32_e64 s[16:17], s55, v186
	v_cmp_gt_u32_e64 s[14:15], s55, v185
	v_cmp_gt_u32_e64 s[12:13], s55, v184
	v_cmp_gt_u32_e64 s[10:11], s55, v183
	v_cmp_gt_u32_e64 s[0:1], s55, v182
	v_subrev_u32_e32 v181, 32, v205
	v_subrev_u32_e32 v180, 32, v204
	v_subrev_u32_e32 v179, 32, v203
	v_subrev_u32_e32 v178, 32, v202
	v_subrev_u32_e32 v177, 32, v193
	v_subrev_u32_e32 v176, 32, v192
	v_subrev_u32_e32 v175, 32, v191
	v_subrev_u32_e32 v174, 32, v190
	v_subrev_u32_e32 v173, 32, v189
	v_subrev_u32_e32 v172, 32, v188
	v_subrev_u32_e32 v141, 32, v187
	v_subrev_u32_e32 v140, 32, v186
	v_subrev_u32_e32 v139, 32, v185
	v_subrev_u32_e32 v138, 32, v184
	v_subrev_u32_e32 v33, 32, v183
	s_cbranch_vccz .LBB0_784
	ds_read_b32 v31, v158 offset:512
	s_and_b64 vcc, s[6:7], s[42:43]
	s_mov_b64 s[90:91], 0
	s_waitcnt lgkmcnt(0)
	v_fmamk_f32 v1, v83, 0x3e38aa3b, v31
	v_fmamk_f32 v2, v84, 0x3e38aa3b, v31
	v_cndmask_b32_e32 v1, v238, v1, vcc
	s_and_b64 vcc, s[6:7], s[40:41]
	v_cndmask_b32_e32 v2, v238, v2, vcc
	v_fmamk_f32 v3, v85, 0x3e38aa3b, v31
	s_and_b64 vcc, s[6:7], s[38:39]
	v_cndmask_b32_e32 v3, v238, v3, vcc
	v_fmamk_f32 v4, v86, 0x3e38aa3b, v31
	s_and_b64 vcc, s[6:7], s[36:37]
	v_cndmask_b32_e32 v4, v238, v4, vcc
	v_fmamk_f32 v5, v87, 0x3e38aa3b, v31
	s_and_b64 vcc, s[6:7], s[34:35]
	v_cndmask_b32_e32 v5, v238, v5, vcc
	v_fmamk_f32 v6, v88, 0x3e38aa3b, v31
	s_and_b64 vcc, s[6:7], s[30:31]
	v_cndmask_b32_e32 v6, v238, v6, vcc
	v_fmamk_f32 v7, v89, 0x3e38aa3b, v31
	s_and_b64 vcc, s[6:7], s[26:27]
	v_cndmask_b32_e32 v7, v238, v7, vcc
	v_fmamk_f32 v8, v90, 0x3e38aa3b, v31
	s_and_b64 vcc, s[6:7], s[24:25]
	v_cndmask_b32_e32 v8, v238, v8, vcc
	v_fmamk_f32 v9, v91, 0x3e38aa3b, v31
	s_and_b64 vcc, s[6:7], s[22:23]
	v_cndmask_b32_e32 v9, v238, v9, vcc
	v_fmamk_f32 v10, v92, 0x3e38aa3b, v31
	s_and_b64 vcc, s[6:7], s[20:21]
	v_cndmask_b32_e32 v10, v238, v10, vcc
	v_fmamk_f32 v11, v93, 0x3e38aa3b, v31
	s_and_b64 vcc, s[6:7], s[18:19]
	v_cndmask_b32_e32 v11, v238, v11, vcc
	v_fmamk_f32 v12, v94, 0x3e38aa3b, v31
	s_and_b64 vcc, s[6:7], s[16:17]
	v_cndmask_b32_e32 v12, v238, v12, vcc
	v_fmamk_f32 v13, v95, 0x3e38aa3b, v31
	s_and_b64 vcc, s[6:7], s[14:15]
	v_cndmask_b32_e32 v13, v238, v13, vcc
	v_fmamk_f32 v14, v96, 0x3e38aa3b, v31
	s_and_b64 vcc, s[6:7], s[12:13]
	v_cndmask_b32_e32 v14, v238, v14, vcc
	v_fmamk_f32 v15, v97, 0x3e38aa3b, v31
	s_and_b64 vcc, s[6:7], s[10:11]
	v_cndmask_b32_e32 v15, v238, v15, vcc
	v_fmamk_f32 v16, v66, 0x3e38aa3b, v31
	s_and_b64 vcc, s[6:7], s[0:1]
	v_cndmask_b32_e32 v16, v238, v16, vcc
	v_cmp_gt_u32_e32 vcc, s55, v181
	v_fmamk_f32 v17, v67, 0x3e38aa3b, v31
	s_and_b64 vcc, s[6:7], vcc
	v_cndmask_b32_e32 v17, v238, v17, vcc
	v_cmp_gt_u32_e32 vcc, s55, v180
	v_fmamk_f32 v18, v68, 0x3e38aa3b, v31
	s_and_b64 vcc, s[6:7], vcc
	v_cndmask_b32_e32 v18, v238, v18, vcc
	v_cmp_gt_u32_e32 vcc, s55, v179
	v_fmamk_f32 v19, v69, 0x3e38aa3b, v31
	s_and_b64 vcc, s[6:7], vcc
	v_cndmask_b32_e32 v19, v238, v19, vcc
	v_cmp_gt_u32_e32 vcc, s55, v178
	v_fmamk_f32 v20, v70, 0x3e38aa3b, v31
	s_and_b64 vcc, s[6:7], vcc
	v_cndmask_b32_e32 v20, v238, v20, vcc
	v_cmp_gt_u32_e32 vcc, s55, v177
	v_fmamk_f32 v21, v71, 0x3e38aa3b, v31
	s_and_b64 vcc, s[6:7], vcc
	v_cndmask_b32_e32 v21, v238, v21, vcc
	v_cmp_gt_u32_e32 vcc, s55, v176
	v_fmamk_f32 v22, v72, 0x3e38aa3b, v31
	s_and_b64 vcc, s[6:7], vcc
	v_cndmask_b32_e32 v22, v238, v22, vcc
	v_cmp_gt_u32_e32 vcc, s55, v175
	v_fmamk_f32 v23, v73, 0x3e38aa3b, v31
	s_and_b64 vcc, s[6:7], vcc
	v_cndmask_b32_e32 v23, v238, v23, vcc
	v_cmp_gt_u32_e32 vcc, s55, v174
	v_fmamk_f32 v24, v74, 0x3e38aa3b, v31
	s_and_b64 vcc, s[6:7], vcc
	v_cndmask_b32_e32 v24, v238, v24, vcc
	v_cmp_gt_u32_e32 vcc, s55, v173
	v_fmamk_f32 v25, v75, 0x3e38aa3b, v31
	s_and_b64 vcc, s[6:7], vcc
	v_cndmask_b32_e32 v25, v238, v25, vcc
	v_cmp_gt_u32_e32 vcc, s55, v172
	v_fmamk_f32 v26, v76, 0x3e38aa3b, v31
	s_and_b64 vcc, s[6:7], vcc
	v_cndmask_b32_e32 v26, v238, v26, vcc
	v_cmp_gt_u32_e32 vcc, s55, v141
	v_fmamk_f32 v27, v77, 0x3e38aa3b, v31
	s_and_b64 vcc, s[6:7], vcc
	v_cndmask_b32_e32 v27, v238, v27, vcc
	v_cmp_gt_u32_e32 vcc, s55, v140
	v_fmamk_f32 v28, v78, 0x3e38aa3b, v31
	s_and_b64 vcc, s[6:7], vcc
	v_cndmask_b32_e32 v28, v238, v28, vcc
	v_cmp_gt_u32_e32 vcc, s55, v139
	v_fmamk_f32 v29, v79, 0x3e38aa3b, v31
	s_and_b64 vcc, s[6:7], vcc
	v_cndmask_b32_e32 v29, v238, v29, vcc
	v_cmp_gt_u32_e32 vcc, s55, v138
	v_fmamk_f32 v30, v80, 0x3e38aa3b, v31
	s_and_b64 vcc, s[6:7], vcc
	v_cndmask_b32_e32 v30, v238, v30, vcc
	v_cmp_gt_u32_e32 vcc, s55, v33
	v_fmamk_f32 v0, v82, 0x3e38aa3b, v31
	v_fmac_f32_e32 v31, 0x3e38aa3b, v81
	s_and_b64 vcc, s[6:7], vcc
	v_cndmask_b32_e64 v0, v238, v0, s[8:9]
	v_cndmask_b32_e32 v31, v238, v31, vcc

; #define LAS __attribute__((address_space(3)))
; DI unsigned pk2(float a, float b) { typedef __bf16 bf2 __attribute__((ext_vector_type(2))); bf2 v; v[0] = (__bf16)a; v[1] = (__bf16)b; return __builtin_bit_cast(unsigned, v); }
; #define MFMA32(a, b, c) __builtin_amdgcn_mfma_f32_32x32x16_bf16((a), (b), (c), 0, 0, 0)
; DI void attn_pv(const LAS bf16_t* Vt, int vstride, const f32x16 (&p)[2], f32x16 (&O)[2], int r, int h) {
; #pragma unroll
;   for (int sub = 0; sub < 2; ++sub)
; #pragma unroll
;     for (int s2 = 0; s2 < 2; ++s2) {
;       u32x4 pp;
; #pragma unroll
;       for (int j = 0; j < 4; ++j) pp[j] = pk2(p[sub][8 * s2 + 2 * j], p[sub][8 * s2 + 2 * j + 1]);
;       const bf16x8 pf = __builtin_bit_cast(bf16x8, pp);
; #pragma unroll
;       for (int dt = 0; dt < 2; ++dt) {
;         const LAS bf16_t* vp = Vt + (dt * 32 + r) * vstride + sub * 32 + 16 * s2 + 4 * h;
;         const s16x4 lo = *(const LAS s16x4*)vp, hi = *(const LAS s16x4*)(vp + 8);
;         const bf16x8 vf = __builtin_shufflevector(lo, hi, 0, 1, 2, 3, 4, 5, 6, 7);
;         O[dt] = MFMA32(vf, pf, O[dt]);
;       }
;     }
; }
.LBB0_788:
	v_add3_u32 v31, s84, v162, v164
	v_add_u32_e32 v33, 0x1000, v31
	ds_read2_b64 v[66:69], v31 offset1:2
	ds_read2_b64 v[70:73], v33 offset0:32 offset1:34
	ds_read2_b64 v[74:77], v31 offset0:4 offset1:6
	ds_read2_b64 v[78:81], v33 offset0:36 offset1:38
	ds_read2_b64 v[82:85], v31 offset0:8 offset1:10
	ds_read2_b64 v[86:89], v33 offset0:40 offset1:42
	ds_read2_b64 v[90:93], v31 offset0:12 offset1:14
	ds_read2_b64 v[94:97], v33 offset0:44 offset1:46
	v_exp_f32_e32 v31, v141
	s_xor_b32 s70, s70, 1
	s_andn2_b64 vcc, exec, s[64:65]
	v_cvt_pk_bf16_f32 v0, v0, v1
	v_cvt_pk_bf16_f32 v1, v2, v3
	v_cvt_pk_bf16_f32 v2, v4, v5
	v_cvt_pk_bf16_f32 v3, v6, v7
	v_cvt_pk_bf16_f32 v4, v8, v9
	v_cvt_pk_bf16_f32 v5, v10, v11
	v_cvt_pk_bf16_f32 v6, v12, v13
	v_cvt_pk_bf16_f32 v7, v14, v15
	s_waitcnt lgkmcnt(6)
	v_mfma_f32_32x32x16_bf16 v[50:65], v[66:69], v[0:3], v[50:65]
	v_mfma_f32_32x32x16_bf16 v[34:49], v[70:73], v[0:3], v[34:49]
	v_cvt_pk_bf16_f32 v8, v16, v17
	v_cvt_pk_bf16_f32 v9, v18, v19
	v_cvt_pk_bf16_f32 v10, v20, v21
	v_cvt_pk_bf16_f32 v11, v22, v23
	s_waitcnt lgkmcnt(4)
	v_mfma_f32_32x32x16_bf16 v[50:65], v[74:77], v[4:7], v[50:65]
	v_mfma_f32_32x32x16_bf16 v[34:49], v[78:81], v[4:7], v[34:49]
	v_cvt_pk_bf16_f32 v12, v24, v25
	v_cvt_pk_bf16_f32 v13, v26, v27
	v_cvt_pk_bf16_f32 v14, v28, v29
	v_cvt_pk_bf16_f32 v15, v30, v31
	v_add_f32_e32 v33, v31, v140
	v_add_f32_e32 v143, v33, v143
	s_waitcnt lgkmcnt(2)
	v_mfma_f32_32x32x16_bf16 v[50:65], v[82:85], v[8:11], v[50:65]
	v_mfma_f32_32x32x16_bf16 v[34:49], v[86:89], v[8:11], v[34:49]
	s_waitcnt lgkmcnt(0)
	v_mfma_f32_32x32x16_bf16 v[50:65], v[90:93], v[12:15], v[50:65]
	v_mfma_f32_32x32x16_bf16 v[34:49], v[94:97], v[12:15], v[34:49]
	s_cbranch_vccz .LBB0_790
	v_mov_b32_e32 v171, v139
	s_branch .LBB0_775

; DI int crow(int reg, int h) { return (reg & 3) + 8 * (reg >> 2) + 4 * h; }
; DI void attn_logits(f32x16 (&s)[2], int t, int tw, int nt, int h, int base, int stride, int dmax, bool ok, const LAS float* btl) {
;     ...
;   } else {
; #pragma unroll
;     for (int sub = 0; sub < 2; ++sub)
; #pragma unroll
;       for (int reg = 0; reg < 16; ++reg) {
;         const int kk = sub * 32 + crow(reg, h); const int d = t - (base + kk * stride);
;         const bool valid = (d >= 0) && (d < dmax) && ok;
;         const int di = d < 0 ? 0 : (d > 128 ? 128 : d);
;         const float bsv = btl[di];
;         const float x = s[sub][reg] * QK_SCALE2 + bsv;
;         s[sub][reg] = valid ? x : -1e30f;
;       }
;   }
; DI void attn_tile(const LAS bf16_t* Ks, const LAS bf16_t* Vt, int vstride, const bf16x8 (&qf)[4], f32x16 (&O)[2], float& m, float& l,
;                   int t, int tw, int nt, int r, int h, int base, int stride, int dmax, bool ok, const LAS float* btl) {
;     ...
;     attn_logits(s, t, tw, nt, h, base, stride, dmax, ok, btl);
;     float mx = -1e30f;
; #pragma unroll
;     for (int sub = 0; sub < 2; ++sub)
; #pragma unroll
;       for (int reg = 0; reg < 16; ++reg) mx = fmaxf(mx, s[sub][reg]);
;     mx = fmaxf(mx, __shfl_xor(mx, 32));
;     mn = fmaxf(m, mx);
.Lwin_near_new:
	v_add3_u32 v33, v157, s15, 63
	v_sub_u32_e32 v33, v33, v68
	v_lshl_add_u32 v214, v33, 2, v158
	v_add_u32_e32 v215, -4, v158
	v_add_u32_e32 v154, 0x200, v158
	v_med3_i32 v33, v214, v215, v154
	v_subrev_u32_e32 v150, 4, v214
	v_med3_i32 v150, v150, v215, v154
	v_subrev_u32_e32 v153, 8, v214
	v_med3_i32 v153, v153, v215, v154
	v_subrev_u32_e32 v193, 12, v214
	v_med3_i32 v193, v193, v215, v154
	v_subrev_u32_e32 v202, 32, v214
	v_med3_i32 v202, v202, v215, v154
	v_subrev_u32_e32 v203, 36, v214
	v_med3_i32 v203, v203, v215, v154
	v_subrev_u32_e32 v204, 40, v214
	v_med3_i32 v204, v204, v215, v154
	v_subrev_u32_e32 v208, 44, v214
	v_med3_i32 v208, v208, v215, v154
	ds_read_b32 v205, v33
	ds_read_b32 v206, v150
	ds_read_b32 v207, v153
	ds_read_b32 v209, v193
	ds_read_b32 v210, v202
	ds_read_b32 v211, v203
	ds_read_b32 v212, v204
	ds_read_b32 v213, v208
	v_subrev_u32_e32 v33, 64, v214
	v_med3_i32 v33, v33, v215, v154
	v_subrev_u32_e32 v150, 68, v214
	v_med3_i32 v150, v150, v215, v154
	v_subrev_u32_e32 v153, 72, v214
	v_med3_i32 v153, v153, v215, v154
	v_subrev_u32_e32 v193, 76, v214
	v_med3_i32 v193, v193, v215, v154
	v_subrev_u32_e32 v202, 96, v214
	v_med3_i32 v202, v202, v215, v154
	v_subrev_u32_e32 v203, 100, v214
	v_med3_i32 v203, v203, v215, v154
	v_subrev_u32_e32 v204, 104, v214
	v_med3_i32 v204, v204, v215, v154
	v_subrev_u32_e32 v208, 108, v214
	v_med3_i32 v208, v208, v215, v154
	ds_read_b32 v171, v33
	ds_read_b32 v172, v150
	ds_read_b32 v173, v153
	ds_read_b32 v174, v193
	ds_read_b32 v176, v202
	ds_read_b32 v178, v203
	ds_read_b32 v181, v204
	ds_read_b32 v185, v208
	s_waitcnt lgkmcnt(8)
	v_fmac_f32_e32 v205, 0x3e38aa3b, v50
	v_fmac_f32_e32 v206, 0x3e38aa3b, v51
	v_fmac_f32_e32 v207, 0x3e38aa3b, v52
	v_fmac_f32_e32 v209, 0x3e38aa3b, v53
	v_fmac_f32_e32 v210, 0x3e38aa3b, v54
	v_fmac_f32_e32 v211, 0x3e38aa3b, v55
	v_fmac_f32_e32 v212, 0x3e38aa3b, v56
	v_fmac_f32_e32 v213, 0x3e38aa3b, v57
	v_subrev_u32_e32 v33, 128, v214
	v_med3_i32 v33, v33, v215, v154
	v_subrev_u32_e32 v150, 132, v214
	v_med3_i32 v150, v150, v215, v154
	v_subrev_u32_e32 v153, 136, v214
	v_med3_i32 v153, v153, v215, v154
	v_subrev_u32_e32 v193, 140, v214
	v_med3_i32 v193, v193, v215, v154
	v_subrev_u32_e32 v202, 160, v214
	v_med3_i32 v202, v202, v215, v154
	v_subrev_u32_e32 v203, 164, v214
	v_med3_i32 v203, v203, v215, v154
	v_subrev_u32_e32 v204, 168, v214
	v_med3_i32 v204, v204, v215, v154
	v_subrev_u32_e32 v208, 172, v214
	v_med3_i32 v208, v208, v215, v154
	ds_read_b32 v179, v33
	ds_read_b32 v182, v150
	ds_read_b32 v184, v153
	ds_read_b32 v186, v193
	ds_read_b32 v189, v202
	ds_read_b32 v190, v203
	ds_read_b32 v191, v204
	ds_read_b32 v192, v208
	s_waitcnt lgkmcnt(8)
	v_fmac_f32_e32 v171, 0x3e38aa3b, v58
	v_fmac_f32_e32 v172, 0x3e38aa3b, v59
	v_fmac_f32_e32 v173, 0x3e38aa3b, v60
	v_fmac_f32_e32 v174, 0x3e38aa3b, v61
	v_fmac_f32_e32 v176, 0x3e38aa3b, v62
	v_fmac_f32_e32 v178, 0x3e38aa3b, v63
	v_fmac_f32_e32 v181, 0x3e38aa3b, v64
	v_fmac_f32_e32 v185, 0x3e38aa3b, v65
	v_subrev_u32_e32 v33, 192, v214
	v_med3_i32 v33, v33, v215, v154
	v_subrev_u32_e32 v150, 196, v214
	v_med3_i32 v150, v150, v215, v154
	v_subrev_u32_e32 v153, 200, v214
	v_med3_i32 v153, v153, v215, v154
	v_subrev_u32_e32 v193, 204, v214
	v_med3_i32 v193, v193, v215, v154
	v_subrev_u32_e32 v202, 224, v214
	v_med3_i32 v202, v202, v215, v154
	v_subrev_u32_e32 v203, 228, v214
	v_med3_i32 v203, v203, v215, v154
	v_subrev_u32_e32 v204, 232, v214
	v_med3_i32 v204, v204, v215, v154
	v_subrev_u32_e32 v208, 236, v214
	v_med3_i32 v208, v208, v215, v154
	ds_read_b32 v175, v33
	ds_read_b32 v177, v150
	ds_read_b32 v180, v153
	ds_read_b32 v183, v193
	ds_read_b32 v187, v202
	ds_read_b32 v188, v203
	ds_read_b32 v152, v204
	ds_read_b32 v155, v208
	s_waitcnt lgkmcnt(8)
	v_fmac_f32_e32 v179, 0x3e38aa3b, v34
	v_fmac_f32_e32 v182, 0x3e38aa3b, v35
	v_fmac_f32_e32 v184, 0x3e38aa3b, v36
	v_fmac_f32_e32 v186, 0x3e38aa3b, v37
	v_fmac_f32_e32 v189, 0x3e38aa3b, v38
	v_fmac_f32_e32 v190, 0x3e38aa3b, v39
	v_fmac_f32_e32 v191, 0x3e38aa3b, v40
	v_fmac_f32_e32 v192, 0x3e38aa3b, v41
	s_waitcnt lgkmcnt(0)
	v_fmac_f32_e32 v175, 0x3e38aa3b, v42
	v_fmac_f32_e32 v177, 0x3e38aa3b, v43
	v_fmac_f32_e32 v180, 0x3e38aa3b, v44
	v_fmac_f32_e32 v183, 0x3e38aa3b, v45
	v_fmac_f32_e32 v187, 0x3e38aa3b, v46
	v_fmac_f32_e32 v188, 0x3e38aa3b, v47
	v_fmac_f32_e32 v152, 0x3e38aa3b, v48
	v_fmac_f32_e32 v155, 0x3e38aa3b, v49
	v_max3_f32 v33, v205, s60, v206
	v_max3_f32 v33, v33, v207, v209
	v_max3_f32 v33, v33, v210, v211
	v_max3_f32 v33, v33, v212, v213
	v_max3_f32 v33, v33, v171, v172
	v_max3_f32 v33, v33, v173, v174
	v_max3_f32 v33, v33, v176, v178
	v_max3_f32 v33, v33, v181, v185
	v_max3_f32 v33, v33, v179, v182
	v_max3_f32 v33, v33, v184, v186
	v_max3_f32 v33, v33, v189, v190
	v_max3_f32 v33, v33, v191, v192
	v_max3_f32 v33, v33, v175, v177
	v_max3_f32 v33, v33, v180, v183
	v_max3_f32 v33, v33, v187, v188
	v_max3_f32 v33, v33, v152, v155
	ds_bpermute_b32 v150, v160, v33
	s_waitcnt lgkmcnt(0)
; DI int crow(int reg, int h) { return (reg & 3) + 8 * (reg >> 2) + 4 * h; }
; DI void attn_logits(f32x16 (&s)[2], int t, int tw, int nt, int h, int base, int stride, int dmax, bool ok, const LAS float* btl) {
;     ...
;   } else {
; #pragma unroll
;     for (int sub = 0; sub < 2; ++sub)
; #pragma unroll
;       for (int reg = 0; reg < 16; ++reg) {
;         const int kk = sub * 32 + crow(reg, h); const int d = t - (base + kk * stride);
;         const bool valid = (d >= 0) && (d < dmax) && ok;
;         const int di = d < 0 ? 0 : (d > 128 ? 128 : d);
;         const float bsv = btl[di];
;         const float x = s[sub][reg] * QK_SCALE2 + bsv;
;         s[sub][reg] = valid ? x : -1e30f;
;       }
;   }
; DI void attn_tile(const LAS bf16_t* Ks, const LAS bf16_t* Vt, int vstride, const bf16x8 (&qf)[4], f32x16 (&O)[2], float& m, float& l,
;                   int t, int tw, int nt, int r, int h, int base, int stride, int dmax, bool ok, const LAS float* btl) {
;     ...
;     mx = fmaxf(mx, __shfl_xor(mx, 32));
;     mn = fmaxf(m, mx);
; #pragma unroll
;     for (int sub = 0; sub < 2; ++sub)
; #pragma unroll
;       for (int reg = 0; reg < 16; ++reg) { const float e = __builtin_amdgcn_exp2f(s[sub][reg] - mn); s[sub][reg] = e; ls += e; }
;   }
	v_max3_f32 v151, v170, v33, v150
	s_nop 0
	v_pk_add_f32 v[172:173], v[172:173], v[150:151] op_sel:[0,1] op_sel_hi:[1,1] neg_lo:[0,1] neg_hi:[0,1]
	v_pk_add_f32 v[174:175], v[174:175], v[150:151] op_sel:[0,1] op_sel_hi:[1,1] neg_lo:[0,1] neg_hi:[0,1]
	v_pk_add_f32 v[176:177], v[176:177], v[150:151] op_sel:[0,1] op_sel_hi:[1,1] neg_lo:[0,1] neg_hi:[0,1]
	v_pk_add_f32 v[178:179], v[178:179], v[150:151] op_sel:[0,1] op_sel_hi:[1,1] neg_lo:[0,1] neg_hi:[0,1]
	v_pk_add_f32 v[180:181], v[180:181], v[150:151] op_sel:[0,1] op_sel_hi:[1,1] neg_lo:[0,1] neg_hi:[0,1]
	v_pk_add_f32 v[182:183], v[182:183], v[150:151] op_sel:[0,1] op_sel_hi:[1,1] neg_lo:[0,1] neg_hi:[0,1]
	v_pk_add_f32 v[184:185], v[184:185], v[150:151] op_sel:[0,1] op_sel_hi:[1,1] neg_lo:[0,1] neg_hi:[0,1]
	v_pk_add_f32 v[186:187], v[186:187], v[150:151] op_sel:[0,1] op_sel_hi:[1,1] neg_lo:[0,1] neg_hi:[0,1]
	v_pk_add_f32 v[188:189], v[188:189], v[150:151] op_sel:[0,1] op_sel_hi:[1,1] neg_lo:[0,1] neg_hi:[0,1]
	v_pk_add_f32 v[190:191], v[190:191], v[150:151] op_sel:[0,1] op_sel_hi:[1,1] neg_lo:[0,1] neg_hi:[0,1]
	v_pk_add_f32 v[206:207], v[206:207], v[150:151] op_sel:[0,1] op_sel_hi:[1,1] neg_lo:[0,1] neg_hi:[0,1]
	v_pk_add_f32 v[210:211], v[210:211], v[150:151] op_sel:[0,1] op_sel_hi:[1,1] neg_lo:[0,1] neg_hi:[0,1]
	v_pk_add_f32 v[212:213], v[212:213], v[150:151] op_sel:[0,1] op_sel_hi:[1,1] neg_lo:[0,1] neg_hi:[0,1]
	v_sub_f32_e32 v152, v152, v151
	v_sub_f32_e32 v155, v155, v151
	v_sub_f32_e32 v171, v171, v151
	v_sub_f32_e32 v192, v192, v151
	v_sub_f32_e32 v205, v205, v151
	v_sub_f32_e32 v209, v209, v151
	v_exp_f32_e32 v205, v205
	v_exp_f32_e32 v206, v206
	v_exp_f32_e32 v207, v207
	v_exp_f32_e32 v209, v209
	v_exp_f32_e32 v210, v210
	v_exp_f32_e32 v211, v211
	v_exp_f32_e32 v212, v212
	v_exp_f32_e32 v213, v213
	v_exp_f32_e32 v171, v171
	v_exp_f32_e32 v172, v172
	v_exp_f32_e32 v173, v173
	v_exp_f32_e32 v174, v174
	v_exp_f32_e32 v176, v176
	v_exp_f32_e32 v178, v178
	v_exp_f32_e32 v181, v181
	v_exp_f32_e32 v185, v185
	v_exp_f32_e32 v179, v179
	v_exp_f32_e32 v182, v182
	v_exp_f32_e32 v184, v184
	v_exp_f32_e32 v186, v186
	v_exp_f32_e32 v189, v189
	v_exp_f32_e32 v190, v190
	v_exp_f32_e32 v191, v191
	v_exp_f32_e32 v192, v192
	v_exp_f32_e32 v175, v175
	v_exp_f32_e32 v177, v177
	v_exp_f32_e32 v180, v180
	v_exp_f32_e32 v183, v183
	v_exp_f32_e32 v187, v187
	v_exp_f32_e32 v188, v188
	v_exp_f32_e32 v152, v152
	v_pk_add_f32 v[202:203], v[172:173], v[174:175]
	v_pk_add_f32 v[214:215], v[176:177], v[178:179]
	v_pk_add_f32 v[202:203], v[202:203], v[180:181]
	v_pk_add_f32 v[214:215], v[214:215], v[182:183]
	v_pk_add_f32 v[202:203], v[202:203], v[184:185]
	v_pk_add_f32 v[214:215], v[214:215], v[186:187]
	v_pk_add_f32 v[202:203], v[202:203], v[188:189]
	v_pk_add_f32 v[214:215], v[214:215], v[190:191]
	v_pk_add_f32 v[202:203], v[202:203], v[206:207]
	v_pk_add_f32 v[214:215], v[214:215], v[210:211]
	v_pk_add_f32 v[202:203], v[202:203], v[212:213]
	s_nop 0
	v_pk_add_f32 v[202:203], v[202:203], v[214:215]
	s_nop 0
	v_add_f32_e32 v154, v202, v203
	v_add_f32_e32 v154, v152, v154
	v_add_f32_e32 v154, v171, v154
	v_add_f32_e32 v154, v192, v154
	v_add_f32_e32 v154, v205, v154
	v_add_f32_e32 v154, v209, v154
	s_branch .LBB0_798
.LBB0_800:
	s_andn2_b64 vcc, exec, s[8:9]
	s_cbranch_vccz .Lwin_near_new
	v_add_u32_e32 v33, s15, v168
	v_add_u32_e32 v205, 63, v33
	v_add_u32_e32 v175, 62, v33
	v_add_u32_e32 v151, 30, v33
	v_add3_u32 v172, v157, s15, 63
	v_cmp_gt_u32_e64 s[6:7], s97, v205
	s_mov_b64 s[12:13], -1
	s_andn2_b64 vcc, exec, s[8:9]
	v_cmp_gt_u32_e64 s[0:1], s97, v175
	v_subrev_u32_e32 v171, 32, v205
	v_cmp_gt_u32_e64 s[8:9], s97, v151
	s_cbranch_vccnz .LBB0_802
	v_med3_i32 v33, v205, 0, v237
	v_lshl_add_u32 v33, v33, 2, v158
	ds_read_b32 v33, v33
	v_sub_u32_e32 v202, v172, v144
	v_med3_i32 v180, v202, 0, v237
	v_lshl_add_u32 v180, v180, 2, v158
	ds_read_b32 v180, v180
	s_waitcnt lgkmcnt(1)
	v_fmac_f32_e32 v33, 0x3e38aa3b, v50
	v_sub_u32_e32 v204, v172, v146
	v_cndmask_b32_e64 v150, v238, v33, s[6:7]
	v_med3_i32 v33, v175, 0, v237
	v_med3_i32 v182, v204, 0, v237
	v_lshl_add_u32 v33, v33, 2, v158
	v_add_u32_e32 v186, s15, v169
	v_lshl_add_u32 v182, v182, 2, v158
	ds_read_b32 v152, v33
	ds_read_b32 v182, v182
	v_add_u32_e32 v33, 63, v186
	v_sub_u32_e32 v189, v172, v138
	v_sub_u32_e32 v207, v172, v76
	v_med3_i32 v153, v33, 0, v237
	v_cmp_gt_u32_e32 vcc, s97, v33
	v_med3_i32 v33, v189, 0, v237
	v_med3_i32 v187, v207, 0, v237
	v_lshl_add_u32 v153, v153, 2, v158
	v_sub_u32_e32 v188, v172, v139
	v_lshl_add_u32 v33, v33, 2, v158
	v_sub_u32_e32 v203, v172, v147
	v_lshl_add_u32 v187, v187, 2, v158
	ds_read_b32 v153, v153
	ds_read_b32 v208, v187
	ds_read_b32 v176, v33
	v_med3_i32 v33, v188, 0, v237
	v_med3_i32 v183, v203, 0, v237
	v_med3_i32 v187, v171, 0, v237
	v_lshl_add_u32 v33, v33, 2, v158
	v_sub_u32_e32 v191, v172, v140
	v_lshl_add_u32 v183, v183, 2, v158
	v_sub_u32_e32 v206, v172, v148
	v_lshl_add_u32 v187, v187, 2, v158
	ds_read_b32 v177, v33
	ds_read_b32 v183, v183
	ds_read_b32 v209, v187
	v_med3_i32 v33, v191, 0, v237
	v_med3_i32 v184, v206, 0, v237
	v_sub_u32_e32 v190, v172, v141
	v_lshl_add_u32 v33, v33, 2, v158
	v_lshl_add_u32 v184, v184, 2, v158
	ds_read_b32 v178, v33
	ds_read_b32 v184, v184
	v_med3_i32 v33, v190, 0, v237
	v_lshl_add_u32 v33, v33, 2, v158
	ds_read_b32 v179, v33
	v_sub_u32_e32 v205, v172, v149
	v_med3_i32 v185, v205, 0, v237
	v_mov_b32_e32 v154, v51
	v_mov_b32_e32 v155, v52
	v_sub_u32_e32 v193, v172, v142
	v_lshl_add_u32 v185, v185, 2, v158
	s_waitcnt lgkmcnt(8)
; DI int crow(int reg, int h) { return (reg & 3) + 8 * (reg >> 2) + 4 * h; }
; DI void attn_logits(f32x16 (&s)[2], int t, int tw, int nt, int h, int base, int stride, int dmax, bool ok, const LAS float* btl) {
;     ...
;   } else {
; #pragma unroll
;     for (int sub = 0; sub < 2; ++sub)
; #pragma unroll
;       for (int reg = 0; reg < 16; ++reg) {
;         const int kk = sub * 32 + crow(reg, h); const int d = t - (base + kk * stride);
;         const bool valid = (d >= 0) && (d < dmax) && ok;
;         const int di = d < 0 ? 0 : (d > 128 ? 128 : d);
;         const float bsv = btl[di];
;         const float x = s[sub][reg] * QK_SCALE2 + bsv;
;         s[sub][reg] = valid ? x : -1e30f;
;       }
;   }
	v_pk_fma_f32 v[152:153], v[154:155], s[80:81], v[152:153] op_sel_hi:[1,0,1]
	v_mov_b32_e32 v154, v53
	v_mov_b32_e32 v155, v54
	ds_read_b32 v185, v185
	v_med3_i32 v33, v193, 0, v237
	v_add_u32_e32 v187, 31, v186
	v_med3_i32 v186, v151, 0, v237
	v_cndmask_b32_e64 v152, v238, v152, s[0:1]
	v_cmp_gt_u32_e64 s[0:1], s97, v189
	s_waitcnt lgkmcnt(6)
	v_pk_fma_f32 v[154:155], v[154:155], s[80:81], v[176:177] op_sel_hi:[1,0,1]
	v_mov_b32_e32 v176, v55
	v_mov_b32_e32 v177, v56
	v_sub_u32_e32 v192, v172, v143
	v_lshl_add_u32 v33, v33, 2, v158
	v_lshl_add_u32 v186, v186, 2, v158
	v_subrev_u32_e32 v189, 32, v189
	v_cndmask_b32_e32 v153, v238, v153, vcc
	v_cmp_gt_u32_e32 vcc, s97, v188
	s_waitcnt lgkmcnt(1)
	v_pk_fma_f32 v[176:177], v[176:177], s[80:81], v[178:179] op_sel_hi:[1,0,1]
	ds_read_b32 v178, v33
	ds_read_b32 v186, v186
	v_med3_i32 v33, v192, 0, v237
	v_subrev_u32_e32 v210, 32, v188
	v_med3_i32 v188, v189, 0, v237
	v_lshl_add_u32 v33, v33, 2, v158
	v_lshl_add_u32 v188, v188, 2, v158
	ds_read_b32 v179, v33
	ds_read_b32 v188, v188
	v_sub_u32_e32 v33, v172, v145
	v_med3_i32 v181, v33, 0, v237
	v_lshl_add_u32 v181, v181, 2, v158
	ds_read_b32 v181, v181
	v_cndmask_b32_e64 v154, v238, v154, s[0:1]
	v_cndmask_b32_e32 v155, v238, v155, vcc
	v_cmp_gt_u32_e32 vcc, s97, v190
	v_cmp_gt_u32_e64 s[0:1], s97, v191
	v_subrev_u32_e32 v191, 32, v191
	v_cndmask_b32_e32 v174, v238, v177, vcc
	v_cndmask_b32_e64 v173, v238, v176, s[0:1]
	v_mov_b32_e32 v176, v57
	v_mov_b32_e32 v177, v58
	v_cmp_gt_u32_e32 vcc, s97, v192
	s_waitcnt lgkmcnt(2)
	v_pk_fma_f32 v[176:177], v[176:177], s[80:81], v[178:179] op_sel_hi:[1,0,1]
	v_mov_b32_e32 v178, v59
	v_mov_b32_e32 v179, v60
	v_cmp_gt_u32_e64 s[0:1], s97, v193
	v_cndmask_b32_e32 v177, v238, v177, vcc
	v_cmp_gt_u32_e32 vcc, s97, v33
	s_waitcnt lgkmcnt(0)
	v_pk_fma_f32 v[178:179], v[178:179], s[80:81], v[180:181] op_sel_hi:[1,0,1]
	v_mov_b32_e32 v180, v61
	v_mov_b32_e32 v181, v62
	v_cndmask_b32_e64 v176, v238, v176, s[0:1]
	v_cmp_gt_u32_e64 s[0:1], s97, v202
	v_cndmask_b32_e32 v179, v238, v179, vcc
	v_cmp_gt_u32_e32 vcc, s97, v203
	v_pk_fma_f32 v[180:181], v[180:181], s[80:81], v[182:183] op_sel_hi:[1,0,1]
	v_mov_b32_e32 v182, v63
	v_mov_b32_e32 v183, v64
	v_cndmask_b32_e64 v178, v238, v178, s[0:1]
	v_cmp_gt_u32_e64 s[0:1], s97, v204
	v_cndmask_b32_e32 v181, v238, v181, vcc
	v_cmp_gt_u32_e32 vcc, s97, v205
	v_pk_fma_f32 v[182:183], v[182:183], s[80:81], v[184:185] op_sel_hi:[1,0,1]
	v_pk_mov_b32 v[184:185], v[64:65], v[34:35] op_sel:[1,0]
	v_cndmask_b32_e64 v180, v238, v180, s[0:1]
	v_cmp_gt_u32_e64 s[0:1], s97, v206
	v_cndmask_b32_e32 v183, v238, v183, vcc
	v_cmp_gt_u32_e32 vcc, s97, v171
	v_pk_fma_f32 v[208:209], v[184:185], s[80:81], v[208:209] op_sel_hi:[1,0,1]
	v_cndmask_b32_e64 v182, v238, v182, s[0:1]
	v_cmp_gt_u32_e64 s[0:1], s97, v207
	v_cndmask_b32_e32 v184, v238, v209, vcc
	v_cmp_gt_u32_e32 vcc, s97, v187
	v_med3_i32 v187, v187, 0, v237
	v_cndmask_b32_e64 v185, v238, v208, s[0:1]
	v_lshl_add_u32 v187, v187, 2, v158
	v_cmp_gt_u32_e64 s[0:1], s97, v189
	v_med3_i32 v189, v210, 0, v237
	ds_read_b32 v187, v187
	v_lshl_add_u32 v189, v189, 2, v158
	ds_read_b32 v189, v189
	v_mov_b32_e32 v208, v35
	v_mov_b32_e32 v209, v36
	s_waitcnt lgkmcnt(1)
	v_pk_fma_f32 v[186:187], v[208:209], s[80:81], v[186:187] op_sel_hi:[1,0,1]
	v_mov_b32_e32 v208, v37
	v_mov_b32_e32 v209, v38
	v_cndmask_b32_e32 v187, v238, v187, vcc
	v_cmp_gt_u32_e32 vcc, s97, v210
	s_waitcnt lgkmcnt(0)
	v_pk_fma_f32 v[188:189], v[208:209], s[80:81], v[188:189] op_sel_hi:[1,0,1]
	v_subrev_u32_e32 v210, 32, v190
	v_cndmask_b32_e64 v188, v238, v188, s[0:1]
	v_med3_i32 v190, v191, 0, v237
	v_cmp_gt_u32_e64 s[0:1], s97, v191
	v_med3_i32 v191, v210, 0, v237
	v_lshl_add_u32 v190, v190, 2, v158
	v_lshl_add_u32 v191, v191, 2, v158
	ds_read_b32 v190, v190
	ds_read_b32 v191, v191
	v_subrev_u32_e32 v193, 32, v193
	v_cndmask_b32_e32 v189, v238, v189, vcc
	v_cmp_gt_u32_e32 vcc, s97, v210
	v_subrev_u32_e32 v210, 32, v192
	v_med3_i32 v192, v193, 0, v237
	v_mov_b32_e32 v208, v39
	v_mov_b32_e32 v209, v40
	v_lshl_add_u32 v192, v192, 2, v158
	ds_read_b32 v192, v192
	s_waitcnt lgkmcnt(1)
	v_pk_fma_f32 v[190:191], v[208:209], s[80:81], v[190:191] op_sel_hi:[1,0,1]
	v_mov_b32_e32 v208, v41
	v_cndmask_b32_e64 v190, v238, v190, s[0:1]
	v_cmp_gt_u32_e64 s[0:1], s97, v193
	v_med3_i32 v193, v210, 0, v237
	v_lshl_add_u32 v193, v193, 2, v158
	ds_read_b32 v193, v193
	v_mov_b32_e32 v209, v42
	v_cndmask_b32_e32 v191, v238, v191, vcc
	v_cmp_gt_u32_e32 vcc, s97, v210
	v_subrev_u32_e32 v33, 32, v33
	s_waitcnt lgkmcnt(0)
	v_pk_fma_f32 v[192:193], v[208:209], s[80:81], v[192:193] op_sel_hi:[1,0,1]
	v_subrev_u32_e32 v202, 32, v202
	v_cndmask_b32_e32 v193, v238, v193, vcc
	v_med3_i32 v210, v202, 0, v237
	v_cmp_gt_u32_e32 vcc, s97, v33
	v_med3_i32 v33, v33, 0, v237
	v_lshl_add_u32 v210, v210, 2, v158
	v_lshl_add_u32 v33, v33, 2, v158
	ds_read_b32 v210, v210
	ds_read_b32 v211, v33
	v_mov_b32_e32 v208, v43
	v_mov_b32_e32 v209, v44
	v_cndmask_b32_e64 v192, v238, v192, s[0:1]
	v_cmp_gt_u32_e64 s[0:1], s97, v202
	s_waitcnt lgkmcnt(0)
	v_pk_fma_f32 v[208:209], v[208:209], s[80:81], v[210:211] op_sel_hi:[1,0,1]
	v_subrev_u32_e32 v33, 32, v203
	v_subrev_u32_e32 v203, 32, v204
	v_cndmask_b32_e64 v202, v238, v208, s[0:1]
	v_cndmask_b32_e32 v208, v238, v209, vcc
	v_med3_i32 v204, v203, 0, v237
	v_cmp_gt_u32_e32 vcc, s97, v33
	v_med3_i32 v33, v33, 0, v237
	v_lshl_add_u32 v204, v204, 2, v158
	v_lshl_add_u32 v33, v33, 2, v158
	ds_read_b32 v212, v204
	ds_read_b32 v213, v33
	v_mov_b32_e32 v210, v45
	v_mov_b32_e32 v211, v46
	v_subrev_u32_e32 v33, 32, v205
	v_subrev_u32_e32 v205, 32, v206
	s_waitcnt lgkmcnt(0)
	v_pk_fma_f32 v[210:211], v[210:211], s[80:81], v[212:213] op_sel_hi:[1,0,1]
	v_med3_i32 v206, v205, 0, v237
	v_cndmask_b32_e32 v204, v238, v211, vcc
	v_cmp_gt_u32_e32 vcc, s97, v33
	v_med3_i32 v33, v33, 0, v237
	v_lshl_add_u32 v206, v206, 2, v158
	v_lshl_add_u32 v33, v33, 2, v158
	ds_read_b32 v212, v206
	ds_read_b32 v213, v33
	v_cmp_gt_u32_e64 s[0:1], s97, v203
	v_mov_b32_e32 v211, v48
	v_subrev_u32_e32 v33, 32, v207
	v_cndmask_b32_e64 v203, v238, v210, s[0:1]
	v_mov_b32_e32 v210, v47
	s_waitcnt lgkmcnt(0)
	v_pk_fma_f32 v[210:211], v[210:211], s[80:81], v[212:213] op_sel_hi:[1,0,1]
	v_cmp_gt_u32_e64 s[0:1], s97, v205
	v_cndmask_b32_e32 v215, v238, v211, vcc
	v_cmp_gt_u32_e32 vcc, s97, v33
	v_med3_i32 v33, v33, 0, v237
	v_lshl_add_u32 v33, v33, 2, v158
	ds_read_b32 v33, v33
	v_cndmask_b32_e64 v186, v238, v186, s[8:9]
	v_cndmask_b32_e64 v214, v238, v210, s[0:1]
	s_mov_b64 s[12:13], 0
	s_waitcnt lgkmcnt(0)
	v_fmac_f32_e32 v33, 0x3e38aa3b, v49
	v_cndmask_b32_e32 v33, v238, v33, vcc
